# v93: mLSTM output pass, K / V^T tile staging at two sites: the second group of four loads (address computation renamed to free registers) issued behind the first group instead of after its LDS writes
# baseline (speedup 1.0000x reference)
.LBB0_175:
	s_ashr_i32 s59, s58, 31
	v_mov_b32_e32 v92, v165
	s_lshl_b64 s[34:35], s[58:59], 11
	s_add_u32 s34, s39, s34
	v_add_u32_e32 v68, 0x200, v92
	v_add_u32_e32 v74, 0x400, v92
	v_add_u32_e32 v76, 0x600, v92
	v_lshlrev_b32_e32 v0, 4, v92
	v_ashrrev_i32_e32 v84, 5, v92
	v_ashrrev_i32_e32 v86, 5, v68
	v_ashrrev_i32_e32 v88, 5, v74
	v_ashrrev_i32_e32 v90, 5, v76
	s_addc_u32 s35, s52, s35
	v_and_b32_e32 v0, 0x1f0, v0
	v_ashrrev_i32_e32 v85, 31, v84
	v_ashrrev_i32_e32 v87, 31, v86
	v_ashrrev_i32_e32 v89, 31, v88
	v_ashrrev_i32_e32 v91, 31, v90
	v_lshl_add_u64 v[82:83], s[34:35], 0, v[0:1]
	v_lshlrev_b64 v[66:67], 11, v[84:85]
	v_lshlrev_b64 v[68:69], 11, v[86:87]
	v_lshlrev_b64 v[74:75], 11, v[88:89]
	v_lshlrev_b64 v[76:77], 11, v[90:91]
	v_lshl_add_u64 v[66:67], v[82:83], 0, v[66:67]
	v_lshl_add_u64 v[70:71], v[82:83], 0, v[68:69]
	v_lshl_add_u64 v[74:75], v[82:83], 0, v[74:75]
	v_lshl_add_u64 v[78:79], v[82:83], 0, v[76:77]
	global_load_dwordx4 v[66:69], v[66:67], off
	s_nop 0
	global_load_dwordx4 v[70:73], v[70:71], off
	s_nop 0
	global_load_dwordx4 v[74:77], v[74:75], off
	s_nop 0
	global_load_dwordx4 v[78:81], v[78:79], off
	v_add_u32_e32 v206, 0x800, v92
	v_add_u32_e32 v208, 0xa00, v92
	v_add_u32_e32 v214, 0xc00, v92
	v_add_u32_e32 v216, 0xe00, v92
	v_ashrrev_i32_e32 v236, 5, v206
	v_ashrrev_i32_e32 v238, 5, v208
	v_ashrrev_i32_e32 v240, 5, v214
	v_ashrrev_i32_e32 v242, 5, v216
	v_ashrrev_i32_e32 v237, 31, v236
	v_ashrrev_i32_e32 v239, 31, v238
	v_ashrrev_i32_e32 v241, 31, v240
	v_ashrrev_i32_e32 v243, 31, v242
	v_lshlrev_b64 v[206:207], 11, v[236:237]
	v_lshlrev_b64 v[208:209], 11, v[238:239]
	v_lshlrev_b64 v[214:215], 11, v[240:241]
	v_lshlrev_b64 v[216:217], 11, v[242:243]
	v_lshl_add_u64 v[206:207], v[82:83], 0, v[206:207]
	v_lshl_add_u64 v[210:211], v[82:83], 0, v[208:209]
	v_lshl_add_u64 v[214:215], v[82:83], 0, v[214:215]
	v_lshl_add_u64 v[218:219], v[82:83], 0, v[216:217]
	global_load_dwordx4 v[206:209], v[206:207], off
	s_nop 0
	global_load_dwordx4 v[210:213], v[210:211], off
	s_nop 0
	global_load_dwordx4 v[214:217], v[214:215], off
	s_nop 0
	global_load_dwordx4 v[218:221], v[218:219], off
	v_add_u32_e32 v0, s95, v0
	v_mad_u64_u32 v[84:85], s[34:35], v84, s90, v[0:1]
	v_mad_u64_u32 v[90:91], s[34:35], v90, s90, v[0:1]
	v_mad_u64_u32 v[86:87], s[34:35], v86, s90, v[0:1]
	v_mad_u64_u32 v[88:89], s[34:35], v88, s90, v[0:1]
	s_waitcnt vmcnt(7)
	ds_write_b128 v84, v[66:69]
	s_waitcnt vmcnt(6)
	ds_write_b128 v86, v[70:73]
	s_waitcnt vmcnt(5)
	ds_write_b128 v88, v[74:77]
	s_waitcnt vmcnt(4)
	ds_write_b128 v90, v[78:81]
	v_mad_u64_u32 v[222:223], s[34:35], v236, s90, v[0:1]
	v_mad_u64_u32 v[236:237], s[34:35], v238, s90, v[0:1]
	v_mad_u64_u32 v[238:239], s[34:35], v240, s90, v[0:1]
	v_mad_u64_u32 v[240:241], s[34:35], v242, s90, v[0:1]
	s_waitcnt vmcnt(3)
	ds_write_b128 v222, v[206:209]
	s_waitcnt vmcnt(2)
	ds_write_b128 v236, v[210:213]
	s_waitcnt vmcnt(1)
	ds_write_b128 v238, v[214:217]
	s_waitcnt vmcnt(0)
	ds_write_b128 v240, v[218:221]
	s_and_b64 s[34:35], s[42:43], exec
	s_cselect_b32 s37, s47, s96
	s_cmp_lg_u32 s37, 0
	s_cselect_b64 s[34:35], -1, 0
	s_or_b64 s[54:55], s[2:3], s[34:35]
	s_or_b32 s34, s36, s97
	s_lshl_b32 s34, s34, 4
	s_add_i32 s37, s34, s37
	s_or_b32 s45, s36, s72
	s_and_b64 s[34:35], s[2:3], exec
	s_cselect_b32 s56, s37, s45
	s_mul_i32 s35, s56, 0x440
	s_mul_hi_i32 s34, s56, 0x440
	s_add_u32 s48, s80, s35
	v_cndmask_b32_e64 v0, 0, 1, s[54:55]
	s_addc_u32 s49, s81, s34
	v_cmp_ne_u32_e64 s[34:35], 1, v0
	s_andn2_b64 vcc, exec, s[54:55]
	v_mov_b32_e32 v192, 0
	s_cbranch_vccnz .LBB0_177
	global_load_dword v192, v1, s[48:49] offset:1024

.LBB0_237:
	s_ashr_i32 s57, s56, 31
	s_lshl_b64 s[36:37], s[56:57], 17
	s_add_u32 s36, s1, s36
	s_addc_u32 s37, s46, s37
	s_and_b64 vcc, exec, s[34:35]
	s_cbranch_vccnz .LBB0_239
	v_mov_b32_e32 v155, v165
	s_waitcnt lgkmcnt(0)
	s_barrier
	s_nop 0
	v_add_u32_e32 v100, 0x200, v155
	v_add_u32_e32 v106, 0x400, v155
	v_add_u32_e32 v108, 0x600, v155
	v_lshlrev_b32_e32 v0, 4, v155
	v_ashrrev_i32_e32 v156, 5, v155
	v_ashrrev_i32_e32 v158, 5, v100
	v_ashrrev_i32_e32 v160, 5, v106
	v_ashrrev_i32_e32 v162, 5, v108
	v_and_b32_e32 v0, 0x1f0, v0
	v_ashrrev_i32_e32 v157, 31, v156
	v_ashrrev_i32_e32 v159, 31, v158
	v_ashrrev_i32_e32 v161, 31, v160
	v_ashrrev_i32_e32 v163, 31, v162
	v_lshl_add_u64 v[134:135], s[36:37], 0, v[0:1]
	v_lshlrev_b64 v[98:99], 9, v[156:157]
	v_lshlrev_b64 v[100:101], 9, v[158:159]
	v_lshlrev_b64 v[106:107], 9, v[160:161]
	v_lshlrev_b64 v[108:109], 9, v[162:163]
	v_lshl_add_u64 v[98:99], v[134:135], 0, v[98:99]
	v_lshl_add_u64 v[102:103], v[134:135], 0, v[100:101]
	v_lshl_add_u64 v[106:107], v[134:135], 0, v[106:107]
	v_lshl_add_u64 v[110:111], v[134:135], 0, v[108:109]
	global_load_dwordx4 v[98:101], v[98:99], off
	s_nop 0
	global_load_dwordx4 v[102:105], v[102:103], off
	s_nop 0
	global_load_dwordx4 v[106:109], v[106:107], off
	s_nop 0
	global_load_dwordx4 v[110:113], v[110:111], off
	v_add_u32_e32 v206, 0x800, v155
	v_add_u32_e32 v208, 0xa00, v155
	v_add_u32_e32 v214, 0xc00, v155
	v_add_u32_e32 v216, 0xe00, v155
	v_ashrrev_i32_e32 v236, 5, v206
	v_ashrrev_i32_e32 v238, 5, v208
	v_ashrrev_i32_e32 v240, 5, v214
	v_ashrrev_i32_e32 v242, 5, v216
	v_ashrrev_i32_e32 v237, 31, v236
	v_ashrrev_i32_e32 v239, 31, v238
	v_ashrrev_i32_e32 v241, 31, v240
	v_ashrrev_i32_e32 v243, 31, v242
	v_lshlrev_b64 v[206:207], 9, v[236:237]
	v_lshlrev_b64 v[208:209], 9, v[238:239]
	v_lshlrev_b64 v[214:215], 9, v[240:241]
	v_lshlrev_b64 v[216:217], 9, v[242:243]
	v_lshl_add_u64 v[206:207], v[134:135], 0, v[206:207]
	v_lshl_add_u64 v[210:211], v[134:135], 0, v[208:209]
	v_lshl_add_u64 v[214:215], v[134:135], 0, v[214:215]
	v_lshl_add_u64 v[218:219], v[134:135], 0, v[216:217]
	global_load_dwordx4 v[206:209], v[206:207], off
	s_nop 0
	global_load_dwordx4 v[210:213], v[210:211], off
	s_nop 0
	global_load_dwordx4 v[214:217], v[214:215], off
	s_nop 0
	global_load_dwordx4 v[218:221], v[218:219], off
	v_add_u32_e32 v0, s95, v0
	v_mad_u64_u32 v[156:157], s[42:43], v156, s90, v[0:1]
	v_mad_u64_u32 v[158:159], s[42:43], v158, s90, v[0:1]
	v_mad_u64_u32 v[160:161], s[42:43], v160, s90, v[0:1]
	v_mad_u64_u32 v[162:163], s[42:43], v162, s90, v[0:1]
	s_waitcnt vmcnt(7)
	ds_write_b128 v156, v[98:101]
	s_waitcnt vmcnt(6)
	ds_write_b128 v158, v[102:105]
	s_waitcnt vmcnt(5)
	ds_write_b128 v160, v[106:109]
	s_waitcnt vmcnt(4)
	ds_write_b128 v162, v[110:113]
	v_mad_u64_u32 v[222:223], s[42:43], v236, s90, v[0:1]
	v_mad_u64_u32 v[236:237], s[42:43], v238, s90, v[0:1]
	v_mad_u64_u32 v[238:239], s[42:43], v240, s90, v[0:1]
	v_mad_u64_u32 v[240:241], s[42:43], v242, s90, v[0:1]
	s_waitcnt vmcnt(3)
	ds_write_b128 v222, v[206:209]
	s_waitcnt vmcnt(2)
	ds_write_b128 v236, v[210:213]
	s_waitcnt vmcnt(1)
	ds_write_b128 v238, v[214:217]
	s_waitcnt vmcnt(0)
	ds_write_b128 v240, v[218:221]
	s_waitcnt lgkmcnt(0)
	s_barrier
